# pool_mix window classes 0 and 1 hand-written: a thread's six items addressed once, loads issued twelve at a time (classes 2-3 stay in the compiled loop)
# baseline (speedup 1.0000x reference)
.Lmix_pool:
	s_mul_i32 s14, s13, 0x18000
	s_add_i32 s6, s6, s14
	s_add_i32 s99, s14, 0x257fff
	s_mov_b32 s101, 6
	v_readlane_b32 s38, v252, 45
	v_readlane_b32 s39, v252, 46
	v_add_u32_e32 v12, s6, v76
	v_mov_b32_e32 v20, 0xaaab
	s_add_u32 s10, s38, 0xd800000
	s_addc_u32 s11, s39, 0
	s_add_u32 s12, s38, 0x9800000
	s_addc_u32 s13, s39, 0
	v_mov_b32_e32 v13, v12
	v_lshrrev_b32_e32 v14, 6, v13
	v_mul_u32_u24_e32 v14, v14, v20
	v_lshrrev_b32_e32 v14, 17, v14
	v_mul_u32_u24_e32 v15, 0xc0, v14
	v_sub_u32_e32 v15, v13, v15
	v_lshrrev_b32_e32 v16, 3, v15
	v_mul_u32_u24_e32 v16, v16, v20
	v_lshrrev_b32_e32 v16, 17, v16
	v_mul_u32_u24_e32 v17, 24, v16
	v_sub_u32_e32 v17, v15, v17
	v_lshl_add_u32 v14, v14, 3, v16
	v_and_b32_e32 v6, 0x1fff, v14
	v_lshlrev_b32_e32 v14, 11, v14
	v_lshl_add_u32 v0, v17, 4, v14
	v_add_u32_e32 v13, 0x4000, v12
	v_lshrrev_b32_e32 v14, 6, v13
	v_mul_u32_u24_e32 v14, v14, v20
	v_lshrrev_b32_e32 v14, 17, v14
	v_mul_u32_u24_e32 v15, 0xc0, v14
	v_sub_u32_e32 v15, v13, v15
	v_lshrrev_b32_e32 v16, 3, v15
	v_mul_u32_u24_e32 v16, v16, v20
	v_lshrrev_b32_e32 v16, 17, v16
	v_mul_u32_u24_e32 v17, 24, v16
	v_sub_u32_e32 v17, v15, v17
	v_lshl_add_u32 v14, v14, 3, v16
	v_and_b32_e32 v7, 0x1fff, v14
	v_lshlrev_b32_e32 v14, 11, v14
	v_lshl_add_u32 v1, v17, 4, v14
	v_add_u32_e32 v13, 0x8000, v12
	v_lshrrev_b32_e32 v14, 6, v13
	v_mul_u32_u24_e32 v14, v14, v20
	v_lshrrev_b32_e32 v14, 17, v14
	v_mul_u32_u24_e32 v15, 0xc0, v14
	v_sub_u32_e32 v15, v13, v15
	v_lshrrev_b32_e32 v16, 3, v15
	v_mul_u32_u24_e32 v16, v16, v20
	v_lshrrev_b32_e32 v16, 17, v16
	v_mul_u32_u24_e32 v17, 24, v16
	v_sub_u32_e32 v17, v15, v17
	v_lshl_add_u32 v14, v14, 3, v16
	v_and_b32_e32 v8, 0x1fff, v14
	v_lshlrev_b32_e32 v14, 11, v14
	v_lshl_add_u32 v2, v17, 4, v14
	v_add_u32_e32 v13, 0xc000, v12
	v_lshrrev_b32_e32 v14, 6, v13
	v_mul_u32_u24_e32 v14, v14, v20
	v_lshrrev_b32_e32 v14, 17, v14
	v_mul_u32_u24_e32 v15, 0xc0, v14
	v_sub_u32_e32 v15, v13, v15
	v_lshrrev_b32_e32 v16, 3, v15
	v_mul_u32_u24_e32 v16, v16, v20
	v_lshrrev_b32_e32 v16, 17, v16
	v_mul_u32_u24_e32 v17, 24, v16
	v_sub_u32_e32 v17, v15, v17
	v_lshl_add_u32 v14, v14, 3, v16
	v_and_b32_e32 v9, 0x1fff, v14
	v_lshlrev_b32_e32 v14, 11, v14
	v_lshl_add_u32 v3, v17, 4, v14
	v_add_u32_e32 v13, 0x10000, v12
	v_lshrrev_b32_e32 v14, 6, v13
	v_mul_u32_u24_e32 v14, v14, v20
	v_lshrrev_b32_e32 v14, 17, v14
	v_mul_u32_u24_e32 v15, 0xc0, v14
	v_sub_u32_e32 v15, v13, v15
	v_lshrrev_b32_e32 v16, 3, v15
	v_mul_u32_u24_e32 v16, v16, v20
	v_lshrrev_b32_e32 v16, 17, v16
	v_mul_u32_u24_e32 v17, 24, v16
	v_sub_u32_e32 v17, v15, v17
	v_lshl_add_u32 v14, v14, 3, v16
	v_and_b32_e32 v10, 0x1fff, v14
	v_lshlrev_b32_e32 v14, 11, v14
	v_lshl_add_u32 v4, v17, 4, v14
	v_add_u32_e32 v13, 0x14000, v12
	v_lshrrev_b32_e32 v14, 6, v13
	v_mul_u32_u24_e32 v14, v14, v20
	v_lshrrev_b32_e32 v14, 17, v14
	v_mul_u32_u24_e32 v15, 0xc0, v14
	v_sub_u32_e32 v15, v13, v15
	v_lshrrev_b32_e32 v16, 3, v15
	v_mul_u32_u24_e32 v16, v16, v20
	v_lshrrev_b32_e32 v16, 17, v16
	v_mul_u32_u24_e32 v17, 24, v16
	v_sub_u32_e32 v17, v15, v17
	v_lshl_add_u32 v14, v14, 3, v16
	v_and_b32_e32 v11, 0x1fff, v14
	v_lshlrev_b32_e32 v14, 11, v14
	v_lshl_add_u32 v5, v17, 4, v14
	v_cmp_lt_u32_e32 vcc, 0, v6
	v_cndmask_b32_e64 v13, 0, 1, vcc
	v_lshlrev_b32_e32 v13, 11, v13
	v_sub_u32_e32 v13, v0, v13
	global_load_dwordx4 v[28:31], v0, s[10:11]
	global_load_dwordx4 v[32:35], v13, s[10:11]
	v_cmp_lt_u32_e32 vcc, 0, v7
	v_cndmask_b32_e64 v13, 0, 1, vcc
	v_lshlrev_b32_e32 v13, 11, v13
	v_sub_u32_e32 v13, v1, v13
	global_load_dwordx4 v[36:39], v1, s[10:11]
	global_load_dwordx4 v[40:43], v13, s[10:11]
	v_cmp_lt_u32_e32 vcc, 0, v8
	v_cndmask_b32_e64 v13, 0, 1, vcc
	v_lshlrev_b32_e32 v13, 11, v13
	v_sub_u32_e32 v13, v2, v13
	global_load_dwordx4 v[44:47], v2, s[10:11]
	global_load_dwordx4 v[48:51], v13, s[10:11]
	v_cmp_lt_u32_e32 vcc, 0, v9
	v_cndmask_b32_e64 v13, 0, 1, vcc
	v_lshlrev_b32_e32 v13, 11, v13
	v_sub_u32_e32 v13, v3, v13
	global_load_dwordx4 v[52:55], v3, s[10:11]
	global_load_dwordx4 v[56:59], v13, s[10:11]
	v_cmp_lt_u32_e32 vcc, 0, v10
	v_cndmask_b32_e64 v13, 0, 1, vcc
	v_lshlrev_b32_e32 v13, 11, v13
	v_sub_u32_e32 v13, v4, v13
	global_load_dwordx4 v[60:63], v4, s[10:11]
	global_load_dwordx4 v[64:67], v13, s[10:11]
	v_cmp_lt_u32_e32 vcc, 0, v11
	v_cndmask_b32_e64 v13, 0, 1, vcc
	v_lshlrev_b32_e32 v13, 11, v13
	v_sub_u32_e32 v13, v5, v13
	global_load_dwordx4 v[68:71], v5, s[10:11]
	global_load_dwordx4 v[72:75], v13, s[10:11]
	s_waitcnt vmcnt(10)
	v_cmp_lt_u32_e32 vcc, 0, v6
	v_cndmask_b32_e64 v104, 0, 1.0, vcc
	v_cndmask_b32_e64 v106, 1.0, 0.5, vcc
	v_mov_b32_e32 v105, v104
	v_mov_b32_e32 v107, v106
	v_lshlrev_b32_e32 v76, 16, v28
	v_and_b32_e32 v77, 0xffff0000, v28
	v_lshlrev_b32_e32 v78, 16, v29
	v_and_b32_e32 v79, 0xffff0000, v29
	v_lshlrev_b32_e32 v80, 16, v30
	v_and_b32_e32 v81, 0xffff0000, v30
	v_lshlrev_b32_e32 v82, 16, v31
	v_and_b32_e32 v83, 0xffff0000, v31
	v_lshlrev_b32_e32 v108, 16, v32
	v_and_b32_e32 v109, 0xffff0000, v32
	v_lshlrev_b32_e32 v110, 16, v33
	v_and_b32_e32 v111, 0xffff0000, v33
	v_lshlrev_b32_e32 v112, 16, v34
	v_and_b32_e32 v113, 0xffff0000, v34
	v_lshlrev_b32_e32 v114, 16, v35
	v_and_b32_e32 v115, 0xffff0000, v35
	v_pk_fma_f32 v[84:85], v[108:109], v[104:105], v[76:77]
	v_pk_fma_f32 v[86:87], v[110:111], v[104:105], v[78:79]
	v_pk_fma_f32 v[88:89], v[112:113], v[104:105], v[80:81]
	v_pk_fma_f32 v[90:91], v[114:115], v[104:105], v[82:83]
	v_pk_fma_f32 v[92:93], v[84:85], v[106:107], v[76:77] neg_lo:[0,0,1] neg_hi:[0,0,1]
	v_pk_fma_f32 v[94:95], v[86:87], v[106:107], v[78:79] neg_lo:[0,0,1] neg_hi:[0,0,1]
	v_pk_fma_f32 v[96:97], v[88:89], v[106:107], v[80:81] neg_lo:[0,0,1] neg_hi:[0,0,1]
	v_pk_fma_f32 v[98:99], v[90:91], v[106:107], v[82:83] neg_lo:[0,0,1] neg_hi:[0,0,1]
	v_cvt_pk_bf16_f32 v100, v92, v93
	v_cvt_pk_bf16_f32 v101, v94, v95
	v_cvt_pk_bf16_f32 v102, v96, v97
	v_cvt_pk_bf16_f32 v103, v98, v99
	global_store_dwordx4 v0, v[100:103], s[12:13]
	s_waitcnt vmcnt(9)
	v_cmp_lt_u32_e32 vcc, 0, v7
	v_cndmask_b32_e64 v104, 0, 1.0, vcc
	v_cndmask_b32_e64 v106, 1.0, 0.5, vcc
	v_mov_b32_e32 v105, v104
	v_mov_b32_e32 v107, v106
	v_lshlrev_b32_e32 v76, 16, v36
	v_and_b32_e32 v77, 0xffff0000, v36
	v_lshlrev_b32_e32 v78, 16, v37
	v_and_b32_e32 v79, 0xffff0000, v37
	v_lshlrev_b32_e32 v80, 16, v38
	v_and_b32_e32 v81, 0xffff0000, v38
	v_lshlrev_b32_e32 v82, 16, v39
	v_and_b32_e32 v83, 0xffff0000, v39
	v_lshlrev_b32_e32 v108, 16, v40
	v_and_b32_e32 v109, 0xffff0000, v40
	v_lshlrev_b32_e32 v110, 16, v41
	v_and_b32_e32 v111, 0xffff0000, v41
	v_lshlrev_b32_e32 v112, 16, v42
	v_and_b32_e32 v113, 0xffff0000, v42
	v_lshlrev_b32_e32 v114, 16, v43
	v_and_b32_e32 v115, 0xffff0000, v43
	v_pk_fma_f32 v[84:85], v[108:109], v[104:105], v[76:77]
	v_pk_fma_f32 v[86:87], v[110:111], v[104:105], v[78:79]
	v_pk_fma_f32 v[88:89], v[112:113], v[104:105], v[80:81]
	v_pk_fma_f32 v[90:91], v[114:115], v[104:105], v[82:83]
	v_pk_fma_f32 v[92:93], v[84:85], v[106:107], v[76:77] neg_lo:[0,0,1] neg_hi:[0,0,1]
	v_pk_fma_f32 v[94:95], v[86:87], v[106:107], v[78:79] neg_lo:[0,0,1] neg_hi:[0,0,1]
	v_pk_fma_f32 v[96:97], v[88:89], v[106:107], v[80:81] neg_lo:[0,0,1] neg_hi:[0,0,1]
	v_pk_fma_f32 v[98:99], v[90:91], v[106:107], v[82:83] neg_lo:[0,0,1] neg_hi:[0,0,1]
	v_cvt_pk_bf16_f32 v100, v92, v93
	v_cvt_pk_bf16_f32 v101, v94, v95
	v_cvt_pk_bf16_f32 v102, v96, v97
	v_cvt_pk_bf16_f32 v103, v98, v99
	global_store_dwordx4 v1, v[100:103], s[12:13]
	s_waitcnt vmcnt(8)
	v_cmp_lt_u32_e32 vcc, 0, v8
	v_cndmask_b32_e64 v104, 0, 1.0, vcc
	v_cndmask_b32_e64 v106, 1.0, 0.5, vcc
	v_mov_b32_e32 v105, v104
	v_mov_b32_e32 v107, v106
	v_lshlrev_b32_e32 v76, 16, v44
	v_and_b32_e32 v77, 0xffff0000, v44
	v_lshlrev_b32_e32 v78, 16, v45
	v_and_b32_e32 v79, 0xffff0000, v45
	v_lshlrev_b32_e32 v80, 16, v46
	v_and_b32_e32 v81, 0xffff0000, v46
	v_lshlrev_b32_e32 v82, 16, v47
	v_and_b32_e32 v83, 0xffff0000, v47
	v_lshlrev_b32_e32 v108, 16, v48
	v_and_b32_e32 v109, 0xffff0000, v48
	v_lshlrev_b32_e32 v110, 16, v49
	v_and_b32_e32 v111, 0xffff0000, v49
	v_lshlrev_b32_e32 v112, 16, v50
	v_and_b32_e32 v113, 0xffff0000, v50
	v_lshlrev_b32_e32 v114, 16, v51
	v_and_b32_e32 v115, 0xffff0000, v51
	v_pk_fma_f32 v[84:85], v[108:109], v[104:105], v[76:77]
	v_pk_fma_f32 v[86:87], v[110:111], v[104:105], v[78:79]
	v_pk_fma_f32 v[88:89], v[112:113], v[104:105], v[80:81]
	v_pk_fma_f32 v[90:91], v[114:115], v[104:105], v[82:83]
	v_pk_fma_f32 v[92:93], v[84:85], v[106:107], v[76:77] neg_lo:[0,0,1] neg_hi:[0,0,1]
	v_pk_fma_f32 v[94:95], v[86:87], v[106:107], v[78:79] neg_lo:[0,0,1] neg_hi:[0,0,1]
	v_pk_fma_f32 v[96:97], v[88:89], v[106:107], v[80:81] neg_lo:[0,0,1] neg_hi:[0,0,1]
	v_pk_fma_f32 v[98:99], v[90:91], v[106:107], v[82:83] neg_lo:[0,0,1] neg_hi:[0,0,1]
	v_cvt_pk_bf16_f32 v100, v92, v93
	v_cvt_pk_bf16_f32 v101, v94, v95
	v_cvt_pk_bf16_f32 v102, v96, v97
	v_cvt_pk_bf16_f32 v103, v98, v99
	global_store_dwordx4 v2, v[100:103], s[12:13]
	s_waitcnt vmcnt(7)
	v_cmp_lt_u32_e32 vcc, 0, v9
	v_cndmask_b32_e64 v104, 0, 1.0, vcc
	v_cndmask_b32_e64 v106, 1.0, 0.5, vcc
	v_mov_b32_e32 v105, v104
	v_mov_b32_e32 v107, v106
	v_lshlrev_b32_e32 v76, 16, v52
	v_and_b32_e32 v77, 0xffff0000, v52
	v_lshlrev_b32_e32 v78, 16, v53
	v_and_b32_e32 v79, 0xffff0000, v53
	v_lshlrev_b32_e32 v80, 16, v54
	v_and_b32_e32 v81, 0xffff0000, v54
	v_lshlrev_b32_e32 v82, 16, v55
	v_and_b32_e32 v83, 0xffff0000, v55
	v_lshlrev_b32_e32 v108, 16, v56
	v_and_b32_e32 v109, 0xffff0000, v56
	v_lshlrev_b32_e32 v110, 16, v57
	v_and_b32_e32 v111, 0xffff0000, v57
	v_lshlrev_b32_e32 v112, 16, v58
	v_and_b32_e32 v113, 0xffff0000, v58
	v_lshlrev_b32_e32 v114, 16, v59
	v_and_b32_e32 v115, 0xffff0000, v59
	v_pk_fma_f32 v[84:85], v[108:109], v[104:105], v[76:77]
	v_pk_fma_f32 v[86:87], v[110:111], v[104:105], v[78:79]
	v_pk_fma_f32 v[88:89], v[112:113], v[104:105], v[80:81]
	v_pk_fma_f32 v[90:91], v[114:115], v[104:105], v[82:83]
	v_pk_fma_f32 v[92:93], v[84:85], v[106:107], v[76:77] neg_lo:[0,0,1] neg_hi:[0,0,1]
	v_pk_fma_f32 v[94:95], v[86:87], v[106:107], v[78:79] neg_lo:[0,0,1] neg_hi:[0,0,1]
	v_pk_fma_f32 v[96:97], v[88:89], v[106:107], v[80:81] neg_lo:[0,0,1] neg_hi:[0,0,1]
	v_pk_fma_f32 v[98:99], v[90:91], v[106:107], v[82:83] neg_lo:[0,0,1] neg_hi:[0,0,1]
	v_cvt_pk_bf16_f32 v100, v92, v93
	v_cvt_pk_bf16_f32 v101, v94, v95
	v_cvt_pk_bf16_f32 v102, v96, v97
	v_cvt_pk_bf16_f32 v103, v98, v99
	global_store_dwordx4 v3, v[100:103], s[12:13]
	s_waitcnt vmcnt(6)
	v_cmp_lt_u32_e32 vcc, 0, v10
	v_cndmask_b32_e64 v104, 0, 1.0, vcc
	v_cndmask_b32_e64 v106, 1.0, 0.5, vcc
	v_mov_b32_e32 v105, v104
	v_mov_b32_e32 v107, v106
	v_lshlrev_b32_e32 v76, 16, v60
	v_and_b32_e32 v77, 0xffff0000, v60
	v_lshlrev_b32_e32 v78, 16, v61
	v_and_b32_e32 v79, 0xffff0000, v61
	v_lshlrev_b32_e32 v80, 16, v62
	v_and_b32_e32 v81, 0xffff0000, v62
	v_lshlrev_b32_e32 v82, 16, v63
	v_and_b32_e32 v83, 0xffff0000, v63
	v_lshlrev_b32_e32 v108, 16, v64
	v_and_b32_e32 v109, 0xffff0000, v64
	v_lshlrev_b32_e32 v110, 16, v65
	v_and_b32_e32 v111, 0xffff0000, v65
	v_lshlrev_b32_e32 v112, 16, v66
	v_and_b32_e32 v113, 0xffff0000, v66
	v_lshlrev_b32_e32 v114, 16, v67
	v_and_b32_e32 v115, 0xffff0000, v67
	v_pk_fma_f32 v[84:85], v[108:109], v[104:105], v[76:77]
	v_pk_fma_f32 v[86:87], v[110:111], v[104:105], v[78:79]
	v_pk_fma_f32 v[88:89], v[112:113], v[104:105], v[80:81]
	v_pk_fma_f32 v[90:91], v[114:115], v[104:105], v[82:83]
	v_pk_fma_f32 v[92:93], v[84:85], v[106:107], v[76:77] neg_lo:[0,0,1] neg_hi:[0,0,1]
	v_pk_fma_f32 v[94:95], v[86:87], v[106:107], v[78:79] neg_lo:[0,0,1] neg_hi:[0,0,1]
	v_pk_fma_f32 v[96:97], v[88:89], v[106:107], v[80:81] neg_lo:[0,0,1] neg_hi:[0,0,1]
	v_pk_fma_f32 v[98:99], v[90:91], v[106:107], v[82:83] neg_lo:[0,0,1] neg_hi:[0,0,1]
	v_cvt_pk_bf16_f32 v100, v92, v93
	v_cvt_pk_bf16_f32 v101, v94, v95
	v_cvt_pk_bf16_f32 v102, v96, v97
	v_cvt_pk_bf16_f32 v103, v98, v99
	global_store_dwordx4 v4, v[100:103], s[12:13]
	s_waitcnt vmcnt(5)
	v_cmp_lt_u32_e32 vcc, 0, v11
	v_cndmask_b32_e64 v104, 0, 1.0, vcc
	v_cndmask_b32_e64 v106, 1.0, 0.5, vcc
	v_mov_b32_e32 v105, v104
	v_mov_b32_e32 v107, v106
	v_lshlrev_b32_e32 v76, 16, v68
	v_and_b32_e32 v77, 0xffff0000, v68
	v_lshlrev_b32_e32 v78, 16, v69
	v_and_b32_e32 v79, 0xffff0000, v69
	v_lshlrev_b32_e32 v80, 16, v70
	v_and_b32_e32 v81, 0xffff0000, v70
	v_lshlrev_b32_e32 v82, 16, v71
	v_and_b32_e32 v83, 0xffff0000, v71
	v_lshlrev_b32_e32 v108, 16, v72
	v_and_b32_e32 v109, 0xffff0000, v72
	v_lshlrev_b32_e32 v110, 16, v73
	v_and_b32_e32 v111, 0xffff0000, v73
	v_lshlrev_b32_e32 v112, 16, v74
	v_and_b32_e32 v113, 0xffff0000, v74
	v_lshlrev_b32_e32 v114, 16, v75
	v_and_b32_e32 v115, 0xffff0000, v75
	v_pk_fma_f32 v[84:85], v[108:109], v[104:105], v[76:77]
	v_pk_fma_f32 v[86:87], v[110:111], v[104:105], v[78:79]
	v_pk_fma_f32 v[88:89], v[112:113], v[104:105], v[80:81]
	v_pk_fma_f32 v[90:91], v[114:115], v[104:105], v[82:83]
	v_pk_fma_f32 v[92:93], v[84:85], v[106:107], v[76:77] neg_lo:[0,0,1] neg_hi:[0,0,1]
	v_pk_fma_f32 v[94:95], v[86:87], v[106:107], v[78:79] neg_lo:[0,0,1] neg_hi:[0,0,1]
	v_pk_fma_f32 v[96:97], v[88:89], v[106:107], v[80:81] neg_lo:[0,0,1] neg_hi:[0,0,1]
	v_pk_fma_f32 v[98:99], v[90:91], v[106:107], v[82:83] neg_lo:[0,0,1] neg_hi:[0,0,1]
	v_cvt_pk_bf16_f32 v100, v92, v93
	v_cvt_pk_bf16_f32 v101, v94, v95
	v_cvt_pk_bf16_f32 v102, v96, v97
	v_cvt_pk_bf16_f32 v103, v98, v99
	global_store_dwordx4 v5, v[100:103], s[12:13]
	global_load_dwordx4 v[28:31], v0, s[10:11] offset:384
	v_cmp_le_u32_e32 vcc, 1, v6
	v_cndmask_b32_e64 v13, 0, 1, vcc
	v_mul_u32_u24_e32 v13, 0x800, v13
	v_sub_u32_e32 v13, v0, v13
	global_load_dwordx4 v[32:35], v13, s[10:11] offset:384
	v_cmp_le_u32_e32 vcc, 2, v6
	v_cndmask_b32_e64 v13, 0, 1, vcc
	v_mul_u32_u24_e32 v13, 0x1000, v13
	v_sub_u32_e32 v13, v0, v13
	global_load_dwordx4 v[36:39], v13, s[10:11] offset:384
	v_cmp_le_u32_e32 vcc, 3, v6
	v_cndmask_b32_e64 v13, 0, 1, vcc
	v_mul_u32_u24_e32 v13, 0x1800, v13
	v_sub_u32_e32 v13, v0, v13
	global_load_dwordx4 v[40:43], v13, s[10:11] offset:384
	global_load_dwordx4 v[44:47], v1, s[10:11] offset:384
	v_cmp_le_u32_e32 vcc, 1, v7
	v_cndmask_b32_e64 v13, 0, 1, vcc
	v_mul_u32_u24_e32 v13, 0x800, v13
	v_sub_u32_e32 v13, v1, v13
	global_load_dwordx4 v[48:51], v13, s[10:11] offset:384
	v_cmp_le_u32_e32 vcc, 2, v7
	v_cndmask_b32_e64 v13, 0, 1, vcc
	v_mul_u32_u24_e32 v13, 0x1000, v13
	v_sub_u32_e32 v13, v1, v13
	global_load_dwordx4 v[52:55], v13, s[10:11] offset:384
	v_cmp_le_u32_e32 vcc, 3, v7
	v_cndmask_b32_e64 v13, 0, 1, vcc
	v_mul_u32_u24_e32 v13, 0x1800, v13
	v_sub_u32_e32 v13, v1, v13
	global_load_dwordx4 v[56:59], v13, s[10:11] offset:384
	global_load_dwordx4 v[60:63], v2, s[10:11] offset:384
	v_cmp_le_u32_e32 vcc, 1, v8
	v_cndmask_b32_e64 v13, 0, 1, vcc
	v_mul_u32_u24_e32 v13, 0x800, v13
	v_sub_u32_e32 v13, v2, v13
	global_load_dwordx4 v[64:67], v13, s[10:11] offset:384
	v_cmp_le_u32_e32 vcc, 2, v8
	v_cndmask_b32_e64 v13, 0, 1, vcc
	v_mul_u32_u24_e32 v13, 0x1000, v13
	v_sub_u32_e32 v13, v2, v13
	global_load_dwordx4 v[68:71], v13, s[10:11] offset:384
	v_cmp_le_u32_e32 vcc, 3, v8
	v_cndmask_b32_e64 v13, 0, 1, vcc
	v_mul_u32_u24_e32 v13, 0x1800, v13
	v_sub_u32_e32 v13, v2, v13
	global_load_dwordx4 v[72:75], v13, s[10:11] offset:384
	s_waitcnt vmcnt(8)
	v_lshlrev_b32_e32 v76, 16, v28
	v_and_b32_e32 v77, 0xffff0000, v28
	v_lshlrev_b32_e32 v78, 16, v29
	v_and_b32_e32 v79, 0xffff0000, v29
	v_lshlrev_b32_e32 v80, 16, v30
	v_and_b32_e32 v81, 0xffff0000, v30
	v_lshlrev_b32_e32 v82, 16, v31
	v_and_b32_e32 v83, 0xffff0000, v31
	v_mov_b32_e32 v84, v76
	v_mov_b32_e32 v85, v77
	v_mov_b32_e32 v86, v78
	v_mov_b32_e32 v87, v79
	v_mov_b32_e32 v88, v80
	v_mov_b32_e32 v89, v81
	v_mov_b32_e32 v90, v82
	v_mov_b32_e32 v91, v83
	v_cmp_le_u32_e32 vcc, 1, v6
	v_cndmask_b32_e64 v104, 0, 1.0, vcc
	v_mov_b32_e32 v105, v104
	v_lshlrev_b32_e32 v108, 16, v32
	v_and_b32_e32 v109, 0xffff0000, v32
	v_lshlrev_b32_e32 v110, 16, v33
	v_and_b32_e32 v111, 0xffff0000, v33
	v_lshlrev_b32_e32 v112, 16, v34
	v_and_b32_e32 v113, 0xffff0000, v34
	v_lshlrev_b32_e32 v114, 16, v35
	v_and_b32_e32 v115, 0xffff0000, v35
	v_pk_fma_f32 v[84:85], v[108:109], v[104:105], v[84:85]
	v_pk_fma_f32 v[86:87], v[110:111], v[104:105], v[86:87]
	v_pk_fma_f32 v[88:89], v[112:113], v[104:105], v[88:89]
	v_pk_fma_f32 v[90:91], v[114:115], v[104:105], v[90:91]
	v_cmp_le_u32_e32 vcc, 2, v6
	v_cndmask_b32_e64 v104, 0, 1.0, vcc
	v_mov_b32_e32 v105, v104
	v_lshlrev_b32_e32 v108, 16, v36
	v_and_b32_e32 v109, 0xffff0000, v36
	v_lshlrev_b32_e32 v110, 16, v37
	v_and_b32_e32 v111, 0xffff0000, v37
	v_lshlrev_b32_e32 v112, 16, v38
	v_and_b32_e32 v113, 0xffff0000, v38
	v_lshlrev_b32_e32 v114, 16, v39
	v_and_b32_e32 v115, 0xffff0000, v39
	v_pk_fma_f32 v[84:85], v[108:109], v[104:105], v[84:85]
	v_pk_fma_f32 v[86:87], v[110:111], v[104:105], v[86:87]
	v_pk_fma_f32 v[88:89], v[112:113], v[104:105], v[88:89]
	v_pk_fma_f32 v[90:91], v[114:115], v[104:105], v[90:91]
	v_cmp_le_u32_e32 vcc, 3, v6
	v_cndmask_b32_e64 v104, 0, 1.0, vcc
	v_mov_b32_e32 v105, v104
	v_lshlrev_b32_e32 v108, 16, v40
	v_and_b32_e32 v109, 0xffff0000, v40
	v_lshlrev_b32_e32 v110, 16, v41
	v_and_b32_e32 v111, 0xffff0000, v41
	v_lshlrev_b32_e32 v112, 16, v42
	v_and_b32_e32 v113, 0xffff0000, v42
	v_lshlrev_b32_e32 v114, 16, v43
	v_and_b32_e32 v115, 0xffff0000, v43
	v_pk_fma_f32 v[84:85], v[108:109], v[104:105], v[84:85]
	v_pk_fma_f32 v[86:87], v[110:111], v[104:105], v[86:87]
	v_pk_fma_f32 v[88:89], v[112:113], v[104:105], v[88:89]
	v_pk_fma_f32 v[90:91], v[114:115], v[104:105], v[90:91]
	v_mov_b32_e32 v106, 1.0
	v_cmp_le_u32_e32 vcc, 1, v6
	v_cndmask_b32_e64 v106, v106, 0.5, vcc
	v_mov_b32_e32 v107, 0x3eaaaaab
	v_cmp_le_u32_e32 vcc, 2, v6
	v_cndmask_b32_e32 v106, v106, v107, vcc
	v_mov_b32_e32 v107, 0x3e800000
	v_cmp_le_u32_e32 vcc, 3, v6
	v_cndmask_b32_e32 v106, v106, v107, vcc
	v_mov_b32_e32 v107, v106
	v_pk_fma_f32 v[92:93], v[84:85], v[106:107], v[76:77] neg_lo:[0,0,1] neg_hi:[0,0,1]
	v_pk_fma_f32 v[94:95], v[86:87], v[106:107], v[78:79] neg_lo:[0,0,1] neg_hi:[0,0,1]
	v_pk_fma_f32 v[96:97], v[88:89], v[106:107], v[80:81] neg_lo:[0,0,1] neg_hi:[0,0,1]
	v_pk_fma_f32 v[98:99], v[90:91], v[106:107], v[82:83] neg_lo:[0,0,1] neg_hi:[0,0,1]
	v_cvt_pk_bf16_f32 v100, v92, v93
	v_cvt_pk_bf16_f32 v101, v94, v95
	v_cvt_pk_bf16_f32 v102, v96, v97
	v_cvt_pk_bf16_f32 v103, v98, v99
	global_store_dwordx4 v0, v[100:103], s[12:13] offset:384
	s_waitcnt vmcnt(5)
	v_lshlrev_b32_e32 v76, 16, v44
	v_and_b32_e32 v77, 0xffff0000, v44
	v_lshlrev_b32_e32 v78, 16, v45
	v_and_b32_e32 v79, 0xffff0000, v45
	v_lshlrev_b32_e32 v80, 16, v46
	v_and_b32_e32 v81, 0xffff0000, v46
	v_lshlrev_b32_e32 v82, 16, v47
	v_and_b32_e32 v83, 0xffff0000, v47
	v_mov_b32_e32 v84, v76
	v_mov_b32_e32 v85, v77
	v_mov_b32_e32 v86, v78
	v_mov_b32_e32 v87, v79
	v_mov_b32_e32 v88, v80
	v_mov_b32_e32 v89, v81
	v_mov_b32_e32 v90, v82
	v_mov_b32_e32 v91, v83
	v_cmp_le_u32_e32 vcc, 1, v7
	v_cndmask_b32_e64 v104, 0, 1.0, vcc
	v_mov_b32_e32 v105, v104
	v_lshlrev_b32_e32 v108, 16, v48
	v_and_b32_e32 v109, 0xffff0000, v48
	v_lshlrev_b32_e32 v110, 16, v49
	v_and_b32_e32 v111, 0xffff0000, v49
	v_lshlrev_b32_e32 v112, 16, v50
	v_and_b32_e32 v113, 0xffff0000, v50
	v_lshlrev_b32_e32 v114, 16, v51
	v_and_b32_e32 v115, 0xffff0000, v51
	v_pk_fma_f32 v[84:85], v[108:109], v[104:105], v[84:85]
	v_pk_fma_f32 v[86:87], v[110:111], v[104:105], v[86:87]
	v_pk_fma_f32 v[88:89], v[112:113], v[104:105], v[88:89]
	v_pk_fma_f32 v[90:91], v[114:115], v[104:105], v[90:91]
	v_cmp_le_u32_e32 vcc, 2, v7
	v_cndmask_b32_e64 v104, 0, 1.0, vcc
	v_mov_b32_e32 v105, v104
	v_lshlrev_b32_e32 v108, 16, v52
	v_and_b32_e32 v109, 0xffff0000, v52
	v_lshlrev_b32_e32 v110, 16, v53
	v_and_b32_e32 v111, 0xffff0000, v53
	v_lshlrev_b32_e32 v112, 16, v54
	v_and_b32_e32 v113, 0xffff0000, v54
	v_lshlrev_b32_e32 v114, 16, v55
	v_and_b32_e32 v115, 0xffff0000, v55
	v_pk_fma_f32 v[84:85], v[108:109], v[104:105], v[84:85]
	v_pk_fma_f32 v[86:87], v[110:111], v[104:105], v[86:87]
	v_pk_fma_f32 v[88:89], v[112:113], v[104:105], v[88:89]
	v_pk_fma_f32 v[90:91], v[114:115], v[104:105], v[90:91]
	v_cmp_le_u32_e32 vcc, 3, v7
	v_cndmask_b32_e64 v104, 0, 1.0, vcc
	v_mov_b32_e32 v105, v104
	v_lshlrev_b32_e32 v108, 16, v56
	v_and_b32_e32 v109, 0xffff0000, v56
	v_lshlrev_b32_e32 v110, 16, v57
	v_and_b32_e32 v111, 0xffff0000, v57
	v_lshlrev_b32_e32 v112, 16, v58
	v_and_b32_e32 v113, 0xffff0000, v58
	v_lshlrev_b32_e32 v114, 16, v59
	v_and_b32_e32 v115, 0xffff0000, v59
	v_pk_fma_f32 v[84:85], v[108:109], v[104:105], v[84:85]
	v_pk_fma_f32 v[86:87], v[110:111], v[104:105], v[86:87]
	v_pk_fma_f32 v[88:89], v[112:113], v[104:105], v[88:89]
	v_pk_fma_f32 v[90:91], v[114:115], v[104:105], v[90:91]
	v_mov_b32_e32 v106, 1.0
	v_cmp_le_u32_e32 vcc, 1, v7
	v_cndmask_b32_e64 v106, v106, 0.5, vcc
	v_mov_b32_e32 v107, 0x3eaaaaab
	v_cmp_le_u32_e32 vcc, 2, v7
	v_cndmask_b32_e32 v106, v106, v107, vcc
	v_mov_b32_e32 v107, 0x3e800000
	v_cmp_le_u32_e32 vcc, 3, v7
	v_cndmask_b32_e32 v106, v106, v107, vcc
	v_mov_b32_e32 v107, v106
	v_pk_fma_f32 v[92:93], v[84:85], v[106:107], v[76:77] neg_lo:[0,0,1] neg_hi:[0,0,1]
	v_pk_fma_f32 v[94:95], v[86:87], v[106:107], v[78:79] neg_lo:[0,0,1] neg_hi:[0,0,1]
	v_pk_fma_f32 v[96:97], v[88:89], v[106:107], v[80:81] neg_lo:[0,0,1] neg_hi:[0,0,1]
	v_pk_fma_f32 v[98:99], v[90:91], v[106:107], v[82:83] neg_lo:[0,0,1] neg_hi:[0,0,1]
	v_cvt_pk_bf16_f32 v100, v92, v93
	v_cvt_pk_bf16_f32 v101, v94, v95
	v_cvt_pk_bf16_f32 v102, v96, v97
	v_cvt_pk_bf16_f32 v103, v98, v99
	global_store_dwordx4 v1, v[100:103], s[12:13] offset:384
	s_waitcnt vmcnt(2)
	v_lshlrev_b32_e32 v76, 16, v60
	v_and_b32_e32 v77, 0xffff0000, v60
	v_lshlrev_b32_e32 v78, 16, v61
	v_and_b32_e32 v79, 0xffff0000, v61
	v_lshlrev_b32_e32 v80, 16, v62
	v_and_b32_e32 v81, 0xffff0000, v62
	v_lshlrev_b32_e32 v82, 16, v63
	v_and_b32_e32 v83, 0xffff0000, v63
	v_mov_b32_e32 v84, v76
	v_mov_b32_e32 v85, v77
	v_mov_b32_e32 v86, v78
	v_mov_b32_e32 v87, v79
	v_mov_b32_e32 v88, v80
	v_mov_b32_e32 v89, v81
	v_mov_b32_e32 v90, v82
	v_mov_b32_e32 v91, v83
	v_cmp_le_u32_e32 vcc, 1, v8
	v_cndmask_b32_e64 v104, 0, 1.0, vcc
	v_mov_b32_e32 v105, v104
	v_lshlrev_b32_e32 v108, 16, v64
	v_and_b32_e32 v109, 0xffff0000, v64
	v_lshlrev_b32_e32 v110, 16, v65
	v_and_b32_e32 v111, 0xffff0000, v65
	v_lshlrev_b32_e32 v112, 16, v66
	v_and_b32_e32 v113, 0xffff0000, v66
	v_lshlrev_b32_e32 v114, 16, v67
	v_and_b32_e32 v115, 0xffff0000, v67
	v_pk_fma_f32 v[84:85], v[108:109], v[104:105], v[84:85]
	v_pk_fma_f32 v[86:87], v[110:111], v[104:105], v[86:87]
	v_pk_fma_f32 v[88:89], v[112:113], v[104:105], v[88:89]
	v_pk_fma_f32 v[90:91], v[114:115], v[104:105], v[90:91]
	v_cmp_le_u32_e32 vcc, 2, v8
	v_cndmask_b32_e64 v104, 0, 1.0, vcc
	v_mov_b32_e32 v105, v104
	v_lshlrev_b32_e32 v108, 16, v68
	v_and_b32_e32 v109, 0xffff0000, v68
	v_lshlrev_b32_e32 v110, 16, v69
	v_and_b32_e32 v111, 0xffff0000, v69
	v_lshlrev_b32_e32 v112, 16, v70
	v_and_b32_e32 v113, 0xffff0000, v70
	v_lshlrev_b32_e32 v114, 16, v71
	v_and_b32_e32 v115, 0xffff0000, v71
	v_pk_fma_f32 v[84:85], v[108:109], v[104:105], v[84:85]
	v_pk_fma_f32 v[86:87], v[110:111], v[104:105], v[86:87]
	v_pk_fma_f32 v[88:89], v[112:113], v[104:105], v[88:89]
	v_pk_fma_f32 v[90:91], v[114:115], v[104:105], v[90:91]
	v_cmp_le_u32_e32 vcc, 3, v8
	v_cndmask_b32_e64 v104, 0, 1.0, vcc
	v_mov_b32_e32 v105, v104
	v_lshlrev_b32_e32 v108, 16, v72
	v_and_b32_e32 v109, 0xffff0000, v72
	v_lshlrev_b32_e32 v110, 16, v73
	v_and_b32_e32 v111, 0xffff0000, v73
	v_lshlrev_b32_e32 v112, 16, v74
	v_and_b32_e32 v113, 0xffff0000, v74
	v_lshlrev_b32_e32 v114, 16, v75
	v_and_b32_e32 v115, 0xffff0000, v75
	v_pk_fma_f32 v[84:85], v[108:109], v[104:105], v[84:85]
	v_pk_fma_f32 v[86:87], v[110:111], v[104:105], v[86:87]
	v_pk_fma_f32 v[88:89], v[112:113], v[104:105], v[88:89]
	v_pk_fma_f32 v[90:91], v[114:115], v[104:105], v[90:91]
	v_mov_b32_e32 v106, 1.0
	v_cmp_le_u32_e32 vcc, 1, v8
	v_cndmask_b32_e64 v106, v106, 0.5, vcc
	v_mov_b32_e32 v107, 0x3eaaaaab
	v_cmp_le_u32_e32 vcc, 2, v8
	v_cndmask_b32_e32 v106, v106, v107, vcc
	v_mov_b32_e32 v107, 0x3e800000
	v_cmp_le_u32_e32 vcc, 3, v8
	v_cndmask_b32_e32 v106, v106, v107, vcc
	v_mov_b32_e32 v107, v106
	v_pk_fma_f32 v[92:93], v[84:85], v[106:107], v[76:77] neg_lo:[0,0,1] neg_hi:[0,0,1]
	v_pk_fma_f32 v[94:95], v[86:87], v[106:107], v[78:79] neg_lo:[0,0,1] neg_hi:[0,0,1]
	v_pk_fma_f32 v[96:97], v[88:89], v[106:107], v[80:81] neg_lo:[0,0,1] neg_hi:[0,0,1]
	v_pk_fma_f32 v[98:99], v[90:91], v[106:107], v[82:83] neg_lo:[0,0,1] neg_hi:[0,0,1]
	v_cvt_pk_bf16_f32 v100, v92, v93
	v_cvt_pk_bf16_f32 v101, v94, v95
	v_cvt_pk_bf16_f32 v102, v96, v97
	v_cvt_pk_bf16_f32 v103, v98, v99
	global_store_dwordx4 v2, v[100:103], s[12:13] offset:384
	global_load_dwordx4 v[28:31], v3, s[10:11] offset:384
	v_cmp_le_u32_e32 vcc, 1, v9
	v_cndmask_b32_e64 v13, 0, 1, vcc
	v_mul_u32_u24_e32 v13, 0x800, v13
	v_sub_u32_e32 v13, v3, v13
	global_load_dwordx4 v[32:35], v13, s[10:11] offset:384
	v_cmp_le_u32_e32 vcc, 2, v9
	v_cndmask_b32_e64 v13, 0, 1, vcc
	v_mul_u32_u24_e32 v13, 0x1000, v13
	v_sub_u32_e32 v13, v3, v13
	global_load_dwordx4 v[36:39], v13, s[10:11] offset:384
	v_cmp_le_u32_e32 vcc, 3, v9
	v_cndmask_b32_e64 v13, 0, 1, vcc
	v_mul_u32_u24_e32 v13, 0x1800, v13
	v_sub_u32_e32 v13, v3, v13
	global_load_dwordx4 v[40:43], v13, s[10:11] offset:384
	global_load_dwordx4 v[44:47], v4, s[10:11] offset:384
	v_cmp_le_u32_e32 vcc, 1, v10
	v_cndmask_b32_e64 v13, 0, 1, vcc
	v_mul_u32_u24_e32 v13, 0x800, v13
	v_sub_u32_e32 v13, v4, v13
	global_load_dwordx4 v[48:51], v13, s[10:11] offset:384
	v_cmp_le_u32_e32 vcc, 2, v10
	v_cndmask_b32_e64 v13, 0, 1, vcc
	v_mul_u32_u24_e32 v13, 0x1000, v13
	v_sub_u32_e32 v13, v4, v13
	global_load_dwordx4 v[52:55], v13, s[10:11] offset:384
	v_cmp_le_u32_e32 vcc, 3, v10
	v_cndmask_b32_e64 v13, 0, 1, vcc
	v_mul_u32_u24_e32 v13, 0x1800, v13
	v_sub_u32_e32 v13, v4, v13
	global_load_dwordx4 v[56:59], v13, s[10:11] offset:384
	global_load_dwordx4 v[60:63], v5, s[10:11] offset:384
	v_cmp_le_u32_e32 vcc, 1, v11
	v_cndmask_b32_e64 v13, 0, 1, vcc
	v_mul_u32_u24_e32 v13, 0x800, v13
	v_sub_u32_e32 v13, v5, v13
	global_load_dwordx4 v[64:67], v13, s[10:11] offset:384
	v_cmp_le_u32_e32 vcc, 2, v11
	v_cndmask_b32_e64 v13, 0, 1, vcc
	v_mul_u32_u24_e32 v13, 0x1000, v13
	v_sub_u32_e32 v13, v5, v13
	global_load_dwordx4 v[68:71], v13, s[10:11] offset:384
	v_cmp_le_u32_e32 vcc, 3, v11
	v_cndmask_b32_e64 v13, 0, 1, vcc
	v_mul_u32_u24_e32 v13, 0x1800, v13
	v_sub_u32_e32 v13, v5, v13
	global_load_dwordx4 v[72:75], v13, s[10:11] offset:384
	s_waitcnt vmcnt(8)
	v_lshlrev_b32_e32 v76, 16, v28
	v_and_b32_e32 v77, 0xffff0000, v28
	v_lshlrev_b32_e32 v78, 16, v29
	v_and_b32_e32 v79, 0xffff0000, v29
	v_lshlrev_b32_e32 v80, 16, v30
	v_and_b32_e32 v81, 0xffff0000, v30
	v_lshlrev_b32_e32 v82, 16, v31
	v_and_b32_e32 v83, 0xffff0000, v31
	v_mov_b32_e32 v84, v76
	v_mov_b32_e32 v85, v77
	v_mov_b32_e32 v86, v78
	v_mov_b32_e32 v87, v79
	v_mov_b32_e32 v88, v80
	v_mov_b32_e32 v89, v81
	v_mov_b32_e32 v90, v82
	v_mov_b32_e32 v91, v83
	v_cmp_le_u32_e32 vcc, 1, v9
	v_cndmask_b32_e64 v104, 0, 1.0, vcc
	v_mov_b32_e32 v105, v104
	v_lshlrev_b32_e32 v108, 16, v32
	v_and_b32_e32 v109, 0xffff0000, v32
	v_lshlrev_b32_e32 v110, 16, v33
	v_and_b32_e32 v111, 0xffff0000, v33
	v_lshlrev_b32_e32 v112, 16, v34
	v_and_b32_e32 v113, 0xffff0000, v34
	v_lshlrev_b32_e32 v114, 16, v35
	v_and_b32_e32 v115, 0xffff0000, v35
	v_pk_fma_f32 v[84:85], v[108:109], v[104:105], v[84:85]
	v_pk_fma_f32 v[86:87], v[110:111], v[104:105], v[86:87]
	v_pk_fma_f32 v[88:89], v[112:113], v[104:105], v[88:89]
	v_pk_fma_f32 v[90:91], v[114:115], v[104:105], v[90:91]
	v_cmp_le_u32_e32 vcc, 2, v9
	v_cndmask_b32_e64 v104, 0, 1.0, vcc
	v_mov_b32_e32 v105, v104
	v_lshlrev_b32_e32 v108, 16, v36
	v_and_b32_e32 v109, 0xffff0000, v36
	v_lshlrev_b32_e32 v110, 16, v37
	v_and_b32_e32 v111, 0xffff0000, v37
	v_lshlrev_b32_e32 v112, 16, v38
	v_and_b32_e32 v113, 0xffff0000, v38
	v_lshlrev_b32_e32 v114, 16, v39
	v_and_b32_e32 v115, 0xffff0000, v39
	v_pk_fma_f32 v[84:85], v[108:109], v[104:105], v[84:85]
	v_pk_fma_f32 v[86:87], v[110:111], v[104:105], v[86:87]
	v_pk_fma_f32 v[88:89], v[112:113], v[104:105], v[88:89]
	v_pk_fma_f32 v[90:91], v[114:115], v[104:105], v[90:91]
	v_cmp_le_u32_e32 vcc, 3, v9
	v_cndmask_b32_e64 v104, 0, 1.0, vcc
	v_mov_b32_e32 v105, v104
	v_lshlrev_b32_e32 v108, 16, v40
	v_and_b32_e32 v109, 0xffff0000, v40
	v_lshlrev_b32_e32 v110, 16, v41
	v_and_b32_e32 v111, 0xffff0000, v41
	v_lshlrev_b32_e32 v112, 16, v42
	v_and_b32_e32 v113, 0xffff0000, v42
	v_lshlrev_b32_e32 v114, 16, v43
	v_and_b32_e32 v115, 0xffff0000, v43
	v_pk_fma_f32 v[84:85], v[108:109], v[104:105], v[84:85]
	v_pk_fma_f32 v[86:87], v[110:111], v[104:105], v[86:87]
	v_pk_fma_f32 v[88:89], v[112:113], v[104:105], v[88:89]
	v_pk_fma_f32 v[90:91], v[114:115], v[104:105], v[90:91]
	v_mov_b32_e32 v106, 1.0
	v_cmp_le_u32_e32 vcc, 1, v9
	v_cndmask_b32_e64 v106, v106, 0.5, vcc
	v_mov_b32_e32 v107, 0x3eaaaaab
	v_cmp_le_u32_e32 vcc, 2, v9
	v_cndmask_b32_e32 v106, v106, v107, vcc
	v_mov_b32_e32 v107, 0x3e800000
	v_cmp_le_u32_e32 vcc, 3, v9
	v_cndmask_b32_e32 v106, v106, v107, vcc
	v_mov_b32_e32 v107, v106
	v_pk_fma_f32 v[92:93], v[84:85], v[106:107], v[76:77] neg_lo:[0,0,1] neg_hi:[0,0,1]
	v_pk_fma_f32 v[94:95], v[86:87], v[106:107], v[78:79] neg_lo:[0,0,1] neg_hi:[0,0,1]
	v_pk_fma_f32 v[96:97], v[88:89], v[106:107], v[80:81] neg_lo:[0,0,1] neg_hi:[0,0,1]
	v_pk_fma_f32 v[98:99], v[90:91], v[106:107], v[82:83] neg_lo:[0,0,1] neg_hi:[0,0,1]
	v_cvt_pk_bf16_f32 v100, v92, v93
	v_cvt_pk_bf16_f32 v101, v94, v95
	v_cvt_pk_bf16_f32 v102, v96, v97
	v_cvt_pk_bf16_f32 v103, v98, v99
	global_store_dwordx4 v3, v[100:103], s[12:13] offset:384
	s_waitcnt vmcnt(5)
	v_lshlrev_b32_e32 v76, 16, v44
	v_and_b32_e32 v77, 0xffff0000, v44
	v_lshlrev_b32_e32 v78, 16, v45
	v_and_b32_e32 v79, 0xffff0000, v45
	v_lshlrev_b32_e32 v80, 16, v46
	v_and_b32_e32 v81, 0xffff0000, v46
	v_lshlrev_b32_e32 v82, 16, v47
	v_and_b32_e32 v83, 0xffff0000, v47
	v_mov_b32_e32 v84, v76
	v_mov_b32_e32 v85, v77
	v_mov_b32_e32 v86, v78
	v_mov_b32_e32 v87, v79
	v_mov_b32_e32 v88, v80
	v_mov_b32_e32 v89, v81
	v_mov_b32_e32 v90, v82
	v_mov_b32_e32 v91, v83
	v_cmp_le_u32_e32 vcc, 1, v10
	v_cndmask_b32_e64 v104, 0, 1.0, vcc
	v_mov_b32_e32 v105, v104
	v_lshlrev_b32_e32 v108, 16, v48
	v_and_b32_e32 v109, 0xffff0000, v48
	v_lshlrev_b32_e32 v110, 16, v49
	v_and_b32_e32 v111, 0xffff0000, v49
	v_lshlrev_b32_e32 v112, 16, v50
	v_and_b32_e32 v113, 0xffff0000, v50
	v_lshlrev_b32_e32 v114, 16, v51
	v_and_b32_e32 v115, 0xffff0000, v51
	v_pk_fma_f32 v[84:85], v[108:109], v[104:105], v[84:85]
	v_pk_fma_f32 v[86:87], v[110:111], v[104:105], v[86:87]
	v_pk_fma_f32 v[88:89], v[112:113], v[104:105], v[88:89]
	v_pk_fma_f32 v[90:91], v[114:115], v[104:105], v[90:91]
	v_cmp_le_u32_e32 vcc, 2, v10
	v_cndmask_b32_e64 v104, 0, 1.0, vcc
	v_mov_b32_e32 v105, v104
	v_lshlrev_b32_e32 v108, 16, v52
	v_and_b32_e32 v109, 0xffff0000, v52
	v_lshlrev_b32_e32 v110, 16, v53
	v_and_b32_e32 v111, 0xffff0000, v53
	v_lshlrev_b32_e32 v112, 16, v54
	v_and_b32_e32 v113, 0xffff0000, v54
	v_lshlrev_b32_e32 v114, 16, v55
	v_and_b32_e32 v115, 0xffff0000, v55
	v_pk_fma_f32 v[84:85], v[108:109], v[104:105], v[84:85]
	v_pk_fma_f32 v[86:87], v[110:111], v[104:105], v[86:87]
	v_pk_fma_f32 v[88:89], v[112:113], v[104:105], v[88:89]
	v_pk_fma_f32 v[90:91], v[114:115], v[104:105], v[90:91]
	v_cmp_le_u32_e32 vcc, 3, v10
	v_cndmask_b32_e64 v104, 0, 1.0, vcc
	v_mov_b32_e32 v105, v104
	v_lshlrev_b32_e32 v108, 16, v56
	v_and_b32_e32 v109, 0xffff0000, v56
	v_lshlrev_b32_e32 v110, 16, v57
	v_and_b32_e32 v111, 0xffff0000, v57
	v_lshlrev_b32_e32 v112, 16, v58
	v_and_b32_e32 v113, 0xffff0000, v58
	v_lshlrev_b32_e32 v114, 16, v59
	v_and_b32_e32 v115, 0xffff0000, v59
	v_pk_fma_f32 v[84:85], v[108:109], v[104:105], v[84:85]
	v_pk_fma_f32 v[86:87], v[110:111], v[104:105], v[86:87]
	v_pk_fma_f32 v[88:89], v[112:113], v[104:105], v[88:89]
	v_pk_fma_f32 v[90:91], v[114:115], v[104:105], v[90:91]
	v_mov_b32_e32 v106, 1.0
	v_cmp_le_u32_e32 vcc, 1, v10
	v_cndmask_b32_e64 v106, v106, 0.5, vcc
	v_mov_b32_e32 v107, 0x3eaaaaab
	v_cmp_le_u32_e32 vcc, 2, v10
	v_cndmask_b32_e32 v106, v106, v107, vcc
	v_mov_b32_e32 v107, 0x3e800000
	v_cmp_le_u32_e32 vcc, 3, v10
	v_cndmask_b32_e32 v106, v106, v107, vcc
	v_mov_b32_e32 v107, v106
	v_pk_fma_f32 v[92:93], v[84:85], v[106:107], v[76:77] neg_lo:[0,0,1] neg_hi:[0,0,1]
	v_pk_fma_f32 v[94:95], v[86:87], v[106:107], v[78:79] neg_lo:[0,0,1] neg_hi:[0,0,1]
	v_pk_fma_f32 v[96:97], v[88:89], v[106:107], v[80:81] neg_lo:[0,0,1] neg_hi:[0,0,1]
	v_pk_fma_f32 v[98:99], v[90:91], v[106:107], v[82:83] neg_lo:[0,0,1] neg_hi:[0,0,1]
	v_cvt_pk_bf16_f32 v100, v92, v93
	v_cvt_pk_bf16_f32 v101, v94, v95
	v_cvt_pk_bf16_f32 v102, v96, v97
	v_cvt_pk_bf16_f32 v103, v98, v99
	global_store_dwordx4 v4, v[100:103], s[12:13] offset:384
	s_waitcnt vmcnt(2)
	v_lshlrev_b32_e32 v76, 16, v60
	v_and_b32_e32 v77, 0xffff0000, v60
	v_lshlrev_b32_e32 v78, 16, v61
	v_and_b32_e32 v79, 0xffff0000, v61
	v_lshlrev_b32_e32 v80, 16, v62
	v_and_b32_e32 v81, 0xffff0000, v62
	v_lshlrev_b32_e32 v82, 16, v63
	v_and_b32_e32 v83, 0xffff0000, v63
	v_mov_b32_e32 v84, v76
	v_mov_b32_e32 v85, v77
	v_mov_b32_e32 v86, v78
	v_mov_b32_e32 v87, v79
	v_mov_b32_e32 v88, v80
	v_mov_b32_e32 v89, v81
	v_mov_b32_e32 v90, v82
	v_mov_b32_e32 v91, v83
	v_cmp_le_u32_e32 vcc, 1, v11
	v_cndmask_b32_e64 v104, 0, 1.0, vcc
	v_mov_b32_e32 v105, v104
	v_lshlrev_b32_e32 v108, 16, v64
	v_and_b32_e32 v109, 0xffff0000, v64
	v_lshlrev_b32_e32 v110, 16, v65
	v_and_b32_e32 v111, 0xffff0000, v65
	v_lshlrev_b32_e32 v112, 16, v66
	v_and_b32_e32 v113, 0xffff0000, v66
	v_lshlrev_b32_e32 v114, 16, v67
	v_and_b32_e32 v115, 0xffff0000, v67
	v_pk_fma_f32 v[84:85], v[108:109], v[104:105], v[84:85]
	v_pk_fma_f32 v[86:87], v[110:111], v[104:105], v[86:87]
	v_pk_fma_f32 v[88:89], v[112:113], v[104:105], v[88:89]
	v_pk_fma_f32 v[90:91], v[114:115], v[104:105], v[90:91]
	v_cmp_le_u32_e32 vcc, 2, v11
	v_cndmask_b32_e64 v104, 0, 1.0, vcc
	v_mov_b32_e32 v105, v104
	v_lshlrev_b32_e32 v108, 16, v68
	v_and_b32_e32 v109, 0xffff0000, v68
	v_lshlrev_b32_e32 v110, 16, v69
	v_and_b32_e32 v111, 0xffff0000, v69
	v_lshlrev_b32_e32 v112, 16, v70
	v_and_b32_e32 v113, 0xffff0000, v70
	v_lshlrev_b32_e32 v114, 16, v71
	v_and_b32_e32 v115, 0xffff0000, v71
	v_pk_fma_f32 v[84:85], v[108:109], v[104:105], v[84:85]
	v_pk_fma_f32 v[86:87], v[110:111], v[104:105], v[86:87]
	v_pk_fma_f32 v[88:89], v[112:113], v[104:105], v[88:89]
	v_pk_fma_f32 v[90:91], v[114:115], v[104:105], v[90:91]
	v_cmp_le_u32_e32 vcc, 3, v11
	v_cndmask_b32_e64 v104, 0, 1.0, vcc
	v_mov_b32_e32 v105, v104
	v_lshlrev_b32_e32 v108, 16, v72
	v_and_b32_e32 v109, 0xffff0000, v72
	v_lshlrev_b32_e32 v110, 16, v73
	v_and_b32_e32 v111, 0xffff0000, v73
	v_lshlrev_b32_e32 v112, 16, v74
	v_and_b32_e32 v113, 0xffff0000, v74
	v_lshlrev_b32_e32 v114, 16, v75
	v_and_b32_e32 v115, 0xffff0000, v75
	v_pk_fma_f32 v[84:85], v[108:109], v[104:105], v[84:85]
	v_pk_fma_f32 v[86:87], v[110:111], v[104:105], v[86:87]
	v_pk_fma_f32 v[88:89], v[112:113], v[104:105], v[88:89]
	v_pk_fma_f32 v[90:91], v[114:115], v[104:105], v[90:91]
	v_mov_b32_e32 v106, 1.0
	v_cmp_le_u32_e32 vcc, 1, v11
	v_cndmask_b32_e64 v106, v106, 0.5, vcc
	v_mov_b32_e32 v107, 0x3eaaaaab
	v_cmp_le_u32_e32 vcc, 2, v11
	v_cndmask_b32_e32 v106, v106, v107, vcc
	v_mov_b32_e32 v107, 0x3e800000
	v_cmp_le_u32_e32 vcc, 3, v11
	v_cndmask_b32_e32 v106, v106, v107, vcc
	v_mov_b32_e32 v107, v106
	v_pk_fma_f32 v[92:93], v[84:85], v[106:107], v[76:77] neg_lo:[0,0,1] neg_hi:[0,0,1]
	v_pk_fma_f32 v[94:95], v[86:87], v[106:107], v[78:79] neg_lo:[0,0,1] neg_hi:[0,0,1]
	v_pk_fma_f32 v[96:97], v[88:89], v[106:107], v[80:81] neg_lo:[0,0,1] neg_hi:[0,0,1]
	v_pk_fma_f32 v[98:99], v[90:91], v[106:107], v[82:83] neg_lo:[0,0,1] neg_hi:[0,0,1]
	v_cvt_pk_bf16_f32 v100, v92, v93
	v_cvt_pk_bf16_f32 v101, v94, v95
	v_cvt_pk_bf16_f32 v102, v96, v97
	v_cvt_pk_bf16_f32 v103, v98, v99
	global_store_dwordx4 v5, v[100:103], s[12:13] offset:384
	s_add_i32 s6, s6, 0x180000
	v_mov_b32_e32 v76, v241
